# GEMM K-loops (input projection, MLA-out, FF1): LDS-DMA loads use SGPR base + 32-bit lane offset, 16 v_lshl_add_u64 per trip removed
# speedup vs baseline: 1.0050x; 1.0050x over previous
; #define PG8_STAGE(bufoff, gbase, voff) do { _Pragma("unroll") for (int _i = 0; _i < 2; ++_i) \
;         __builtin_amdgcn_global_load_lds((const unsigned*)((const char*)(gbase) + (voff)[_i]), (PG8_LAS unsigned*)(lds + (bufoff) + ldsw + _i * 8192), 16, 0, 0); } while (0)
; #define PG8_LDA(dst, b, h) do { _Pragma("unroll") for (int m = 0; m < 4; ++m) _Pragma("unroll") for (int k = 0; k < 2; ++k) dst[m][k] = *(const PG8_LAS bf16x8*)(lds + PG8_SA(b, h) + aoff + m * 2048 + k * 1024); } while (0)
; #define PG8_LDB(dst, b, h) do { _Pragma("unroll") for (int n = 0; n < 2; ++n) _Pragma("unroll") for (int k = 0; k < 2; ++k) dst[n][k] = *(const PG8_LAS bf16x8*)(lds + PG8_SB(b, h) + boff + n * 2048 + k * 1024); } while (0)
; #define PG8_MMA(ai, bj, At, Bt) do { __builtin_amdgcn_s_setprio(1); _Pragma("unroll") for (int m = 0; m < 4; ++m) _Pragma("unroll") for (int n = 0; n < 2; ++n) _Pragma("unroll") for (int k = 0; k < 2; ++k) \
;         acc[ai][bj][m][n] = __builtin_amdgcn_mfma_f32_16x16x32_bf16(Bt[n][k], At[m][k], acc[ai][bj][m][n], 0, 0, 0); __builtin_amdgcn_s_setprio(0); } while (0)
; #define PG8_WAIT_V(n) asm volatile("s_waitcnt vmcnt(" #n ")" ::: "memory")
; #define PG8_WAIT_L(n) asm volatile("s_waitcnt lgkmcnt(" #n ")" ::: "memory")
; #define PG8_BAR __builtin_amdgcn_s_barrier()
; #define PG8_SCHED __builtin_amdgcn_sched_barrier(0)
; template <class Epi, class Sched, bool ALIGN_EPI = false, bool SP2 = false>
; __device__ __forceinline__ void gemm_phase(PG8_LAS unsigned char* lds, int tid_in, const Gemm g, const Sched& S, const Epi& E) {
;     ...
;             PG8_LDB(B0, 0, 0); PG8_LDB(B1, 0, 1); PG8_SCHED; PG8_LDA(At, 0, 0); PG8_STAGE(PG8_SA(1, 1), a1 + hstep, voffA);
;             PG8_WAIT_V(8); PG8_WAIT_L(0); PG8_BAR; PG8_MMA(0, 0, At, B0); PG8_MMA(0, 1, At, B1); PG8_BAR; PG8_SCHED;
;             PG8_LDA(At, 0, 1); PG8_STAGE(PG8_SB(0, 0), b2, voffB); PG8_STAGE(PG8_SB(0, 1), b2 + hstep, voffB); PG8_STAGE(PG8_SA(0, 0), a2, voffA);
;             PG8_WAIT_V(8); PG8_WAIT_L(0); PG8_BAR; PG8_MMA(1, 0, At, B0); PG8_MMA(1, 1, At, B1); PG8_BAR; PG8_SCHED;
.LBB0_137:
	s_add_u32 s18, s34, 0xfffc0080
	s_addc_u32 s33, s35, -1
	s_add_i32 s36, 0, 0x10000
	s_cmp_eq_u32 s29, 12
	s_cselect_b32 s49, s1, s33
	s_cselect_b32 s48, s15, s18
	s_cselect_b32 s43, s13, s28
	s_cselect_b32 s42, s20, s21
	s_add_i32 s18, 0, 0x14000
	v_add_u32_e32 v142, s36, v162
	v_add_u32_e32 v160, s18, v162
	ds_read_b128 v[130:133], v142
	ds_read_b128 v[134:137], v142 offset:1024
	ds_read_b128 v[138:141], v142 offset:2048
	ds_read_b128 v[142:145], v142 offset:3072
	ds_read_b128 v[156:159], v160
	ds_read_b128 v[164:167], v160 offset:1024
	ds_read_b128 v[168:171], v160 offset:2048
	ds_read_b128 v[172:175], v160 offset:3072
	s_add_i32 m0, s51, 0xc000
	ds_read_b128 v[176:179], v163
	ds_read_b128 v[180:183], v163 offset:1024
	ds_read_b128 v[184:187], v163 offset:2048
	ds_read_b128 v[188:191], v163 offset:3072
	ds_read_b128 v[192:195], v163 offset:4096
	ds_read_b128 v[196:199], v163 offset:5120
	ds_read_b128 v[200:203], v163 offset:6144
	ds_read_b128 v[218:221], v163 offset:7168
	global_load_lds_dwordx4 v152, s[34:35]
	s_add_i32 m0, s51, 0xe000
	s_nop 0
	global_load_lds_dwordx4 v154, s[34:35]
	s_waitcnt vmcnt(8)
	s_waitcnt lgkmcnt(0)
	s_barrier
	s_setprio 1
	s_waitcnt lgkmcnt(0)
	v_mfma_f32_16x16x32_bf16 v[126:129], v[130:133], v[176:179], v[126:129]
	v_mfma_f32_16x16x32_bf16 v[122:125], v[138:141], v[176:179], v[122:125]
	v_mfma_f32_16x16x32_bf16 v[118:121], v[130:133], v[184:187], v[118:121]
	v_mfma_f32_16x16x32_bf16 v[110:113], v[138:141], v[184:187], v[110:113]
	v_mfma_f32_16x16x32_bf16 v[102:105], v[130:133], v[192:195], v[102:105]
	v_mfma_f32_16x16x32_bf16 v[94:97], v[138:141], v[192:195], v[94:97]
	v_mfma_f32_16x16x32_bf16 v[86:89], v[130:133], v[200:203], v[86:89]
	v_mfma_f32_16x16x32_bf16 v[78:81], v[138:141], v[200:203], v[78:81]
	v_mfma_f32_16x16x32_bf16 v[126:129], v[134:137], v[180:183], v[126:129]
	v_mfma_f32_16x16x32_bf16 v[122:125], v[142:145], v[180:183], v[122:125]
	v_mfma_f32_16x16x32_bf16 v[118:121], v[134:137], v[188:191], v[118:121]
	v_mfma_f32_16x16x32_bf16 v[110:113], v[142:145], v[188:191], v[110:113]
	v_mfma_f32_16x16x32_bf16 v[102:105], v[134:137], v[196:199], v[102:105]
	v_mfma_f32_16x16x32_bf16 v[94:97], v[142:145], v[196:199], v[94:97]
	v_mfma_f32_16x16x32_bf16 v[86:89], v[134:137], v[218:221], v[86:89]
	v_mfma_f32_16x16x32_bf16 v[78:81], v[142:145], v[218:221], v[78:81]
	v_mfma_f32_16x16x32_bf16 v[114:117], v[156:159], v[176:179], v[114:117]
	v_mfma_f32_16x16x32_bf16 v[106:109], v[168:171], v[176:179], v[106:109]
	v_mfma_f32_16x16x32_bf16 v[98:101], v[156:159], v[184:187], v[98:101]
	v_mfma_f32_16x16x32_bf16 v[90:93], v[168:171], v[184:187], v[90:93]
	v_mfma_f32_16x16x32_bf16 v[82:85], v[156:159], v[192:195], v[82:85]
	v_mfma_f32_16x16x32_bf16 v[74:77], v[168:171], v[192:195], v[74:77]
	v_mfma_f32_16x16x32_bf16 v[70:73], v[156:159], v[200:203], v[70:73]
	v_mfma_f32_16x16x32_bf16 v[66:69], v[168:171], v[200:203], v[66:69]
	v_mfma_f32_16x16x32_bf16 v[114:117], v[164:167], v[180:183], v[114:117]
	v_mfma_f32_16x16x32_bf16 v[106:109], v[172:175], v[180:183], v[106:109]
	v_mfma_f32_16x16x32_bf16 v[98:101], v[164:167], v[188:191], v[98:101]
	v_mfma_f32_16x16x32_bf16 v[90:93], v[172:175], v[188:191], v[90:93]
	v_mfma_f32_16x16x32_bf16 v[82:85], v[164:167], v[196:199], v[82:85]
	v_mfma_f32_16x16x32_bf16 v[74:77], v[172:175], v[196:199], v[74:77]
	v_mfma_f32_16x16x32_bf16 v[70:73], v[164:167], v[218:221], v[70:73]
	v_mfma_f32_16x16x32_bf16 v[66:69], v[172:175], v[218:221], v[66:69]
	s_setprio 0
	s_barrier
	s_add_i32 s33, s36, s50
	s_mov_b32 m0, s33
	ds_read_b128 v[176:179], v163 offset:16384
	ds_read_b128 v[180:183], v163 offset:17408
	ds_read_b128 v[184:187], v163 offset:18432
	ds_read_b128 v[188:191], v163 offset:19456
	ds_read_b128 v[192:195], v163 offset:20480
	ds_read_b128 v[196:199], v163 offset:21504
	ds_read_b128 v[200:203], v163 offset:22528
	ds_read_b128 v[218:221], v163 offset:23552
	global_load_lds_dwordx4 v8, s[42:43]
	s_add_i32 m0, s33, 0x2000
	s_add_u32 s36, s42, 0x40000
	s_addc_u32 s37, s43, 0
	s_add_i32 s18, s18, s50
	global_load_lds_dwordx4 v146, s[42:43]
	s_mov_b32 m0, s18
	s_nop 0
	global_load_lds_dwordx4 v8, s[36:37]
	s_add_i32 m0, s18, 0x2000
	s_nop 0
	global_load_lds_dwordx4 v146, s[36:37]
	s_mov_b32 m0, s51
	s_nop 0
	global_load_lds_dwordx4 v150, s[48:49]
	s_mov_b32 m0, s58
	s_nop 0
	global_load_lds_dwordx4 v148, s[48:49]
	s_waitcnt vmcnt(8)
	s_waitcnt lgkmcnt(0)
	s_barrier
	s_setprio 1
	s_waitcnt lgkmcnt(0)
	v_mfma_f32_16x16x32_bf16 v[62:65], v[130:133], v[176:179], v[62:65]
	v_mfma_f32_16x16x32_bf16 v[58:61], v[138:141], v[176:179], v[58:61]
	v_mfma_f32_16x16x32_bf16 v[54:57], v[130:133], v[184:187], v[54:57]
	v_mfma_f32_16x16x32_bf16 v[46:49], v[138:141], v[184:187], v[46:49]
	v_mfma_f32_16x16x32_bf16 v[38:41], v[130:133], v[192:195], v[38:41]
	v_mfma_f32_16x16x32_bf16 v[30:33], v[138:141], v[192:195], v[30:33]
	v_mfma_f32_16x16x32_bf16 v[22:25], v[130:133], v[200:203], v[22:25]
	v_mfma_f32_16x16x32_bf16 v[14:17], v[138:141], v[200:203], v[14:17]
	v_mfma_f32_16x16x32_bf16 v[62:65], v[134:137], v[180:183], v[62:65]
	v_mfma_f32_16x16x32_bf16 v[58:61], v[142:145], v[180:183], v[58:61]
	v_mfma_f32_16x16x32_bf16 v[54:57], v[134:137], v[188:191], v[54:57]
	v_mfma_f32_16x16x32_bf16 v[46:49], v[142:145], v[188:191], v[46:49]
	v_mfma_f32_16x16x32_bf16 v[38:41], v[134:137], v[196:199], v[38:41]
	v_mfma_f32_16x16x32_bf16 v[30:33], v[142:145], v[196:199], v[30:33]
	v_mfma_f32_16x16x32_bf16 v[22:25], v[134:137], v[218:221], v[22:25]
	v_mfma_f32_16x16x32_bf16 v[14:17], v[142:145], v[218:221], v[14:17]
	v_mfma_f32_16x16x32_bf16 v[50:53], v[156:159], v[176:179], v[50:53]
	v_mfma_f32_16x16x32_bf16 v[42:45], v[168:171], v[176:179], v[42:45]
	v_mfma_f32_16x16x32_bf16 v[34:37], v[156:159], v[184:187], v[34:37]
	v_mfma_f32_16x16x32_bf16 v[26:29], v[168:171], v[184:187], v[26:29]
	v_mfma_f32_16x16x32_bf16 v[18:21], v[156:159], v[192:195], v[18:21]
	v_mfma_f32_16x16x32_bf16 v[10:13], v[168:171], v[192:195], v[10:13]
	v_mfma_f32_16x16x32_bf16 v[4:7], v[156:159], v[200:203], v[4:7]
	v_mfma_f32_16x16x32_bf16 v[0:3], v[168:171], v[200:203], v[0:3]
	v_mfma_f32_16x16x32_bf16 v[50:53], v[164:167], v[180:183], v[50:53]
	v_mfma_f32_16x16x32_bf16 v[42:45], v[172:175], v[180:183], v[42:45]
	v_mfma_f32_16x16x32_bf16 v[34:37], v[164:167], v[188:191], v[34:37]
	v_mfma_f32_16x16x32_bf16 v[26:29], v[172:175], v[188:191], v[26:29]
	v_mfma_f32_16x16x32_bf16 v[18:21], v[164:167], v[196:199], v[18:21]
	v_mfma_f32_16x16x32_bf16 v[10:13], v[172:175], v[196:199], v[10:13]
	v_mfma_f32_16x16x32_bf16 v[4:7], v[164:167], v[218:221], v[4:7]
	v_mfma_f32_16x16x32_bf16 v[0:3], v[172:175], v[218:221], v[0:3]
	s_setprio 0
	s_barrier
; #define PG8_STAGE(bufoff, gbase, voff) do { _Pragma("unroll") for (int _i = 0; _i < 2; ++_i) \
;         __builtin_amdgcn_global_load_lds((const unsigned*)((const char*)(gbase) + (voff)[_i]), (PG8_LAS unsigned*)(lds + (bufoff) + ldsw + _i * 8192), 16, 0, 0); } while (0)
; #define PG8_LDA(dst, b, h) do { _Pragma("unroll") for (int m = 0; m < 4; ++m) _Pragma("unroll") for (int k = 0; k < 2; ++k) dst[m][k] = *(const PG8_LAS bf16x8*)(lds + PG8_SA(b, h) + aoff + m * 2048 + k * 1024); } while (0)
; #define PG8_LDB(dst, b, h) do { _Pragma("unroll") for (int n = 0; n < 2; ++n) _Pragma("unroll") for (int k = 0; k < 2; ++k) dst[n][k] = *(const PG8_LAS bf16x8*)(lds + PG8_SB(b, h) + boff + n * 2048 + k * 1024); } while (0)
; #define PG8_MMA(ai, bj, At, Bt) do { __builtin_amdgcn_s_setprio(1); _Pragma("unroll") for (int m = 0; m < 4; ++m) _Pragma("unroll") for (int n = 0; n < 2; ++n) _Pragma("unroll") for (int k = 0; k < 2; ++k) \
;         acc[ai][bj][m][n] = __builtin_amdgcn_mfma_f32_16x16x32_bf16(Bt[n][k], At[m][k], acc[ai][bj][m][n], 0, 0, 0); __builtin_amdgcn_s_setprio(0); } while (0)
; #define PG8_WAIT_V(n) asm volatile("s_waitcnt vmcnt(" #n ")" ::: "memory")
; #define PG8_WAIT_L(n) asm volatile("s_waitcnt lgkmcnt(" #n ")" ::: "memory")
; #define PG8_BAR __builtin_amdgcn_s_barrier()
; #define PG8_SCHED __builtin_amdgcn_sched_barrier(0)
; template <class Epi, class Sched, bool ALIGN_EPI = false, bool SP2 = false>
; __device__ __forceinline__ void gemm_phase(PG8_LAS unsigned char* lds, int tid_in, const Gemm g, const Sched& S, const Epi& E) {
;     ...
;             PG8_LDB(B0, 1, 0); PG8_LDB(B1, 1, 1); PG8_SCHED; PG8_LDA(At, 1, 0); PG8_STAGE(PG8_SA(0, 1), a2 + hstep, voffA);
;             PG8_WAIT_V(8); PG8_WAIT_L(0); PG8_BAR; PG8_MMA(0, 0, At, B0); PG8_MMA(0, 1, At, B1); PG8_BAR; PG8_SCHED;
	s_add_i32 s18, 0, 0x18000
	s_add_i32 s33, 0, 0x1c000
	v_add_u32_e32 v142, s18, v162
	v_add_u32_e32 v172, s33, v162
	ds_read_b128 v[130:133], v142
	ds_read_b128 v[134:137], v142 offset:1024
	ds_read_b128 v[138:141], v142 offset:2048
	ds_read_b128 v[142:145], v142 offset:3072
	ds_read_b128 v[156:159], v172
	ds_read_b128 v[164:167], v172 offset:1024
	ds_read_b128 v[168:171], v172 offset:2048
	ds_read_b128 v[172:175], v172 offset:3072
	s_add_u32 s36, s48, 0x40000
	s_addc_u32 s37, s49, 0
	s_mov_b32 m0, s59
	ds_read_b128 v[176:179], v163 offset:32768
	ds_read_b128 v[180:183], v163 offset:33792
	ds_read_b128 v[184:187], v163 offset:34816
	ds_read_b128 v[188:191], v163 offset:35840
	ds_read_b128 v[192:195], v163 offset:36864
	ds_read_b128 v[196:199], v163 offset:37888
	ds_read_b128 v[200:203], v163 offset:38912
	ds_read_b128 v[218:221], v163 offset:39936
	global_load_lds_dwordx4 v150, s[36:37]
	s_mov_b32 m0, s60
	s_nop 0
	global_load_lds_dwordx4 v148, s[36:37]
	s_waitcnt vmcnt(8)
	s_waitcnt lgkmcnt(0)
	s_barrier
	s_setprio 1
	s_waitcnt lgkmcnt(0)
	v_mfma_f32_16x16x32_bf16 v[126:129], v[130:133], v[176:179], v[126:129]
	v_mfma_f32_16x16x32_bf16 v[122:125], v[138:141], v[176:179], v[122:125]
	v_mfma_f32_16x16x32_bf16 v[118:121], v[130:133], v[184:187], v[118:121]
	v_mfma_f32_16x16x32_bf16 v[110:113], v[138:141], v[184:187], v[110:113]
	v_mfma_f32_16x16x32_bf16 v[102:105], v[130:133], v[192:195], v[102:105]
	v_mfma_f32_16x16x32_bf16 v[94:97], v[138:141], v[192:195], v[94:97]
	v_mfma_f32_16x16x32_bf16 v[86:89], v[130:133], v[200:203], v[86:89]
	v_mfma_f32_16x16x32_bf16 v[78:81], v[138:141], v[200:203], v[78:81]
	v_mfma_f32_16x16x32_bf16 v[126:129], v[134:137], v[180:183], v[126:129]
	v_mfma_f32_16x16x32_bf16 v[122:125], v[142:145], v[180:183], v[122:125]
	v_mfma_f32_16x16x32_bf16 v[118:121], v[134:137], v[188:191], v[118:121]
	v_mfma_f32_16x16x32_bf16 v[110:113], v[142:145], v[188:191], v[110:113]
	v_mfma_f32_16x16x32_bf16 v[102:105], v[134:137], v[196:199], v[102:105]
	v_mfma_f32_16x16x32_bf16 v[94:97], v[142:145], v[196:199], v[94:97]
	v_mfma_f32_16x16x32_bf16 v[86:89], v[134:137], v[218:221], v[86:89]
	v_mfma_f32_16x16x32_bf16 v[78:81], v[142:145], v[218:221], v[78:81]
	v_mfma_f32_16x16x32_bf16 v[114:117], v[156:159], v[176:179], v[114:117]
	v_mfma_f32_16x16x32_bf16 v[106:109], v[168:171], v[176:179], v[106:109]
	v_mfma_f32_16x16x32_bf16 v[98:101], v[156:159], v[184:187], v[98:101]
	v_mfma_f32_16x16x32_bf16 v[90:93], v[168:171], v[184:187], v[90:93]
	v_mfma_f32_16x16x32_bf16 v[82:85], v[156:159], v[192:195], v[82:85]
	v_mfma_f32_16x16x32_bf16 v[74:77], v[168:171], v[192:195], v[74:77]
	v_mfma_f32_16x16x32_bf16 v[70:73], v[156:159], v[200:203], v[70:73]
	v_mfma_f32_16x16x32_bf16 v[66:69], v[168:171], v[200:203], v[66:69]
	v_mfma_f32_16x16x32_bf16 v[114:117], v[164:167], v[180:183], v[114:117]
	v_mfma_f32_16x16x32_bf16 v[106:109], v[172:175], v[180:183], v[106:109]
	v_mfma_f32_16x16x32_bf16 v[98:101], v[164:167], v[188:191], v[98:101]
	v_mfma_f32_16x16x32_bf16 v[90:93], v[172:175], v[188:191], v[90:93]
	v_mfma_f32_16x16x32_bf16 v[82:85], v[164:167], v[196:199], v[82:85]
	v_mfma_f32_16x16x32_bf16 v[74:77], v[172:175], v[196:199], v[74:77]
	v_mfma_f32_16x16x32_bf16 v[70:73], v[164:167], v[218:221], v[70:73]
	v_mfma_f32_16x16x32_bf16 v[66:69], v[172:175], v[218:221], v[66:69]
	s_setprio 0
	s_barrier
; #define PG8_STAGE(bufoff, gbase, voff) do { _Pragma("unroll") for (int _i = 0; _i < 2; ++_i) \
;         __builtin_amdgcn_global_load_lds((const unsigned*)((const char*)(gbase) + (voff)[_i]), (PG8_LAS unsigned*)(lds + (bufoff) + ldsw + _i * 8192), 16, 0, 0); } while (0)
; #define PG8_LDA(dst, b, h) do { _Pragma("unroll") for (int m = 0; m < 4; ++m) _Pragma("unroll") for (int k = 0; k < 2; ++k) dst[m][k] = *(const PG8_LAS bf16x8*)(lds + PG8_SA(b, h) + aoff + m * 2048 + k * 1024); } while (0)
; #define PG8_MMA(ai, bj, At, Bt) do { __builtin_amdgcn_s_setprio(1); _Pragma("unroll") for (int m = 0; m < 4; ++m) _Pragma("unroll") for (int n = 0; n < 2; ++n) _Pragma("unroll") for (int k = 0; k < 2; ++k) \
;         acc[ai][bj][m][n] = __builtin_amdgcn_mfma_f32_16x16x32_bf16(Bt[n][k], At[m][k], acc[ai][bj][m][n], 0, 0, 0); __builtin_amdgcn_s_setprio(0); } while (0)
; #define PG8_WAIT_V(n) asm volatile("s_waitcnt vmcnt(" #n ")" ::: "memory")
; #define PG8_WAIT_L(n) asm volatile("s_waitcnt lgkmcnt(" #n ")" ::: "memory")
; #define PG8_BAR __builtin_amdgcn_s_barrier()
; #define PG8_SCHED __builtin_amdgcn_sched_barrier(0)
; template <class Epi, class Sched, bool ALIGN_EPI = false, bool SP2 = false>
; __device__ __forceinline__ void gemm_phase(PG8_LAS unsigned char* lds, int tid_in, const Gemm g, const Sched& S, const Epi& E) {
;     ...
;         for (int t = 0; t < nt; t += 2) {
;     ...
;             PG8_LDA(At, 1, 1); PG8_STAGE(PG8_SB(1, 0), b3, voffB); PG8_STAGE(PG8_SB(1, 1), b3 + hstep, voffB); PG8_STAGE(PG8_SA(1, 0), a3, voffA);
;             PG8_WAIT_V(8); PG8_WAIT_L(0); PG8_BAR; PG8_MMA(1, 0, At, B0); PG8_MMA(1, 1, At, B1); PG8_BAR; PG8_SCHED;
	s_add_i32 s18, s18, s50
	s_mov_b32 m0, s18
	ds_read_b128 v[176:179], v163 offset:49152
	ds_read_b128 v[180:183], v163 offset:50176
	ds_read_b128 v[184:187], v163 offset:51200
	ds_read_b128 v[188:191], v163 offset:52224
	ds_read_b128 v[192:195], v163 offset:53248
	ds_read_b128 v[196:199], v163 offset:54272
	ds_read_b128 v[200:203], v163 offset:55296
	ds_read_b128 v[218:221], v163 offset:56320
	s_add_u32 s42, s42, 0x80
	s_addc_u32 s43, s43, 0
	global_load_lds_dwordx4 v8, s[42:43]
	s_sub_u32 s42, s42, 0x80
	s_subb_u32 s43, s43, 0
	s_add_i32 m0, s18, 0x2000
	s_add_u32 s36, s42, 0x40080
	s_addc_u32 s37, s43, 0
	s_add_i32 s18, s33, s50
	s_add_u32 s42, s42, 0x80
	s_addc_u32 s43, s43, 0
	global_load_lds_dwordx4 v146, s[42:43]
	s_sub_u32 s42, s42, 0x80
	s_subb_u32 s43, s43, 0
	s_mov_b32 m0, s18
	s_nop 0
	global_load_lds_dwordx4 v8, s[36:37]
	s_add_i32 m0, s18, 0x2000
	s_nop 0
	global_load_lds_dwordx4 v146, s[36:37]
	s_mov_b32 m0, s7
	s_nop 0
	s_add_u32 s48, s48, 0x80
	s_addc_u32 s49, s49, 0
	global_load_lds_dwordx4 v150, s[48:49]
	s_sub_u32 s48, s48, 0x80
	s_subb_u32 s49, s49, 0
	s_mov_b32 m0, s8
	s_nop 0
	s_add_u32 s48, s48, 0x80
	s_addc_u32 s49, s49, 0
	global_load_lds_dwordx4 v148, s[48:49]
	s_sub_u32 s48, s48, 0x80
	s_subb_u32 s49, s49, 0
	s_waitcnt vmcnt(8)
	s_waitcnt lgkmcnt(0)
	s_barrier
	s_setprio 1
	s_waitcnt lgkmcnt(0)
	v_mfma_f32_16x16x32_bf16 v[62:65], v[130:133], v[176:179], v[62:65]
	v_mfma_f32_16x16x32_bf16 v[58:61], v[138:141], v[176:179], v[58:61]
	v_mfma_f32_16x16x32_bf16 v[54:57], v[130:133], v[184:187], v[54:57]
	v_mfma_f32_16x16x32_bf16 v[46:49], v[138:141], v[184:187], v[46:49]
	v_mfma_f32_16x16x32_bf16 v[38:41], v[130:133], v[192:195], v[38:41]
	v_mfma_f32_16x16x32_bf16 v[30:33], v[138:141], v[192:195], v[30:33]
	v_mfma_f32_16x16x32_bf16 v[22:25], v[130:133], v[200:203], v[22:25]
	v_mfma_f32_16x16x32_bf16 v[14:17], v[138:141], v[200:203], v[14:17]
	v_mfma_f32_16x16x32_bf16 v[62:65], v[134:137], v[180:183], v[62:65]
	v_mfma_f32_16x16x32_bf16 v[58:61], v[142:145], v[180:183], v[58:61]
	v_mfma_f32_16x16x32_bf16 v[54:57], v[134:137], v[188:191], v[54:57]
	v_mfma_f32_16x16x32_bf16 v[46:49], v[142:145], v[188:191], v[46:49]
	v_mfma_f32_16x16x32_bf16 v[38:41], v[134:137], v[196:199], v[38:41]
	v_mfma_f32_16x16x32_bf16 v[30:33], v[142:145], v[196:199], v[30:33]
	v_mfma_f32_16x16x32_bf16 v[22:25], v[134:137], v[218:221], v[22:25]
	v_mfma_f32_16x16x32_bf16 v[14:17], v[142:145], v[218:221], v[14:17]
	v_mfma_f32_16x16x32_bf16 v[50:53], v[156:159], v[176:179], v[50:53]
	v_mfma_f32_16x16x32_bf16 v[42:45], v[168:171], v[176:179], v[42:45]
	v_mfma_f32_16x16x32_bf16 v[34:37], v[156:159], v[184:187], v[34:37]
	v_mfma_f32_16x16x32_bf16 v[26:29], v[168:171], v[184:187], v[26:29]
	v_mfma_f32_16x16x32_bf16 v[18:21], v[156:159], v[192:195], v[18:21]
	v_mfma_f32_16x16x32_bf16 v[10:13], v[168:171], v[192:195], v[10:13]
	v_mfma_f32_16x16x32_bf16 v[4:7], v[156:159], v[200:203], v[4:7]
	v_mfma_f32_16x16x32_bf16 v[0:3], v[168:171], v[200:203], v[0:3]
	v_mfma_f32_16x16x32_bf16 v[50:53], v[164:167], v[180:183], v[50:53]
	v_mfma_f32_16x16x32_bf16 v[42:45], v[172:175], v[180:183], v[42:45]
	v_mfma_f32_16x16x32_bf16 v[34:37], v[164:167], v[188:191], v[34:37]
	v_mfma_f32_16x16x32_bf16 v[26:29], v[172:175], v[188:191], v[26:29]
	v_mfma_f32_16x16x32_bf16 v[18:21], v[164:167], v[196:199], v[18:21]
	v_mfma_f32_16x16x32_bf16 v[10:13], v[172:175], v[196:199], v[10:13]
	v_mfma_f32_16x16x32_bf16 v[4:7], v[164:167], v[218:221], v[4:7]
	v_mfma_f32_16x16x32_bf16 v[0:3], v[172:175], v[218:221], v[0:3]
	s_setprio 0
	s_barrier
	s_add_i32 s29, s29, 2
	s_add_u32 s34, s34, 0x100
	s_addc_u32 s35, s35, 0
	s_add_u32 s21, s21, 0x100
	s_addc_u32 s28, s28, 0
	s_cmp_gt_u32 s29, 13
	s_cbranch_scc0 .LBB0_137
	s_and_b64 vcc, exec, s[10:11]
	s_cbranch_vccz .LBB0_140
	s_barrier

; #define PG8_STAGE(bufoff, gbase, voff) do { _Pragma("unroll") for (int _i = 0; _i < 2; ++_i) \
;         __builtin_amdgcn_global_load_lds((const unsigned*)((const char*)(gbase) + (voff)[_i]), (PG8_LAS unsigned*)(lds + (bufoff) + ldsw + _i * 8192), 16, 0, 0); } while (0)
; #define PG8_LDA(dst, b, h) do { _Pragma("unroll") for (int m = 0; m < 4; ++m) _Pragma("unroll") for (int k = 0; k < 2; ++k) dst[m][k] = *(const PG8_LAS bf16x8*)(lds + PG8_SA(b, h) + aoff + m * 2048 + k * 1024); } while (0)
; #define PG8_LDB(dst, b, h) do { _Pragma("unroll") for (int n = 0; n < 2; ++n) _Pragma("unroll") for (int k = 0; k < 2; ++k) dst[n][k] = *(const PG8_LAS bf16x8*)(lds + PG8_SB(b, h) + boff + n * 2048 + k * 1024); } while (0)
; #define PG8_MMA(ai, bj, At, Bt) do { __builtin_amdgcn_s_setprio(1); _Pragma("unroll") for (int m = 0; m < 4; ++m) _Pragma("unroll") for (int n = 0; n < 2; ++n) _Pragma("unroll") for (int k = 0; k < 2; ++k) \
;         acc[ai][bj][m][n] = __builtin_amdgcn_mfma_f32_16x16x32_bf16(Bt[n][k], At[m][k], acc[ai][bj][m][n], 0, 0, 0); __builtin_amdgcn_s_setprio(0); } while (0)
; #define PG8_WAIT_V(n) asm volatile("s_waitcnt vmcnt(" #n ")" ::: "memory")
; #define PG8_WAIT_L(n) asm volatile("s_waitcnt lgkmcnt(" #n ")" ::: "memory")
; #define PG8_BAR __builtin_amdgcn_s_barrier()
; #define PG8_SCHED __builtin_amdgcn_sched_barrier(0)
; template <class Epi, class Sched, bool ALIGN_EPI = false, bool SP2 = false>
; __device__ __forceinline__ void gemm_phase(PG8_LAS unsigned char* lds, int tid_in, const Gemm g, const Sched& S, const Epi& E) {
;     ...
;             PG8_LDB(B0, 0, 0); PG8_LDB(B1, 0, 1); PG8_SCHED; PG8_LDA(At, 0, 0); PG8_STAGE(PG8_SA(1, 1), a1 + hstep, voffA);
;             PG8_WAIT_V(8); PG8_WAIT_L(0); PG8_BAR; PG8_MMA(0, 0, At, B0); PG8_MMA(0, 1, At, B1); PG8_BAR; PG8_SCHED;
;             PG8_LDA(At, 0, 1); PG8_STAGE(PG8_SB(0, 0), b2, voffB); PG8_STAGE(PG8_SB(0, 1), b2 + hstep, voffB); PG8_STAGE(PG8_SA(0, 0), a2, voffA);
;             PG8_WAIT_V(8); PG8_WAIT_L(0); PG8_BAR; PG8_MMA(1, 0, At, B0); PG8_MMA(1, 1, At, B1); PG8_BAR; PG8_SCHED;
.LBB0_592:
	s_add_u32 s18, s34, 0xfffe0080
	s_addc_u32 s42, s35, -1
	s_add_i32 s55, 0, 0x10000
	s_cmp_eq_u32 s37, 4
	s_cselect_b32 s49, s15, s42
	s_cselect_b32 s48, s53, s18
	s_cselect_b32 s43, s13, s36
	s_cselect_b32 s42, s38, s39
	s_add_i32 s18, 0, 0x14000
	v_add_u32_e32 v134, s55, v228
	v_add_u32_e32 v158, s18, v228
	ds_read_b128 v[118:121], v134
	ds_read_b128 v[126:129], v134 offset:1024
	ds_read_b128 v[130:133], v134 offset:2048
	ds_read_b128 v[134:137], v134 offset:3072
	ds_read_b128 v[138:141], v158
	ds_read_b128 v[150:153], v158 offset:1024
	ds_read_b128 v[154:157], v158 offset:2048
	ds_read_b128 v[158:161], v158 offset:3072
	s_add_i32 m0, s21, 0xc000
	ds_read_b128 v[162:165], v229
	ds_read_b128 v[166:169], v229 offset:1024
	ds_read_b128 v[170:173], v229 offset:2048
	ds_read_b128 v[174:177], v229 offset:3072
	ds_read_b128 v[178:181], v229 offset:4096
	ds_read_b128 v[182:185], v229 offset:5120
	ds_read_b128 v[186:189], v229 offset:6144
	ds_read_b128 v[200:203], v229 offset:7168
	global_load_lds_dwordx4 v196, s[34:35]
	s_add_i32 m0, s21, 0xe000
	s_nop 0
	global_load_lds_dwordx4 v198, s[34:35]
	s_waitcnt vmcnt(8)
	s_waitcnt lgkmcnt(0)
	s_barrier
	s_setprio 1
	s_waitcnt lgkmcnt(0)
	v_mfma_f32_16x16x32_bf16 v[146:149], v[118:121], v[162:165], v[146:149]
	v_mfma_f32_16x16x32_bf16 v[142:145], v[130:133], v[162:165], v[142:145]
	v_mfma_f32_16x16x32_bf16 v[110:113], v[118:121], v[170:173], v[110:113]
	v_mfma_f32_16x16x32_bf16 v[106:109], v[130:133], v[170:173], v[106:109]
	v_mfma_f32_16x16x32_bf16 v[94:97], v[118:121], v[178:181], v[94:97]
	v_mfma_f32_16x16x32_bf16 v[90:93], v[130:133], v[178:181], v[90:93]
	v_mfma_f32_16x16x32_bf16 v[78:81], v[118:121], v[186:189], v[78:81]
	v_mfma_f32_16x16x32_bf16 v[74:77], v[130:133], v[186:189], v[74:77]
	v_mfma_f32_16x16x32_bf16 v[146:149], v[126:129], v[166:169], v[146:149]
	v_mfma_f32_16x16x32_bf16 v[142:145], v[134:137], v[166:169], v[142:145]
	v_mfma_f32_16x16x32_bf16 v[110:113], v[126:129], v[174:177], v[110:113]
	v_mfma_f32_16x16x32_bf16 v[106:109], v[134:137], v[174:177], v[106:109]
	v_mfma_f32_16x16x32_bf16 v[94:97], v[126:129], v[182:185], v[94:97]
	v_mfma_f32_16x16x32_bf16 v[90:93], v[134:137], v[182:185], v[90:93]
	v_mfma_f32_16x16x32_bf16 v[78:81], v[126:129], v[200:203], v[78:81]
	v_mfma_f32_16x16x32_bf16 v[74:77], v[134:137], v[200:203], v[74:77]
	v_mfma_f32_16x16x32_bf16 v[122:125], v[138:141], v[162:165], v[122:125]
	v_mfma_f32_16x16x32_bf16 v[114:117], v[154:157], v[162:165], v[114:117]
	v_mfma_f32_16x16x32_bf16 v[102:105], v[138:141], v[170:173], v[102:105]
	v_mfma_f32_16x16x32_bf16 v[98:101], v[154:157], v[170:173], v[98:101]
	v_mfma_f32_16x16x32_bf16 v[86:89], v[138:141], v[178:181], v[86:89]
	v_mfma_f32_16x16x32_bf16 v[82:85], v[154:157], v[178:181], v[82:85]
	v_mfma_f32_16x16x32_bf16 v[70:73], v[138:141], v[186:189], v[70:73]
	v_mfma_f32_16x16x32_bf16 v[66:69], v[154:157], v[186:189], v[66:69]
	v_mfma_f32_16x16x32_bf16 v[122:125], v[150:153], v[166:169], v[122:125]
	v_mfma_f32_16x16x32_bf16 v[114:117], v[158:161], v[166:169], v[114:117]
	v_mfma_f32_16x16x32_bf16 v[102:105], v[150:153], v[174:177], v[102:105]
	v_mfma_f32_16x16x32_bf16 v[98:101], v[158:161], v[174:177], v[98:101]
	v_mfma_f32_16x16x32_bf16 v[86:89], v[150:153], v[182:185], v[86:89]
	v_mfma_f32_16x16x32_bf16 v[82:85], v[158:161], v[182:185], v[82:85]
	v_mfma_f32_16x16x32_bf16 v[70:73], v[150:153], v[200:203], v[70:73]
	v_mfma_f32_16x16x32_bf16 v[66:69], v[158:161], v[200:203], v[66:69]
	s_setprio 0
	s_barrier
	s_add_i32 s55, s55, s20
	s_mov_b32 m0, s55
	ds_read_b128 v[162:165], v229 offset:16384
	ds_read_b128 v[166:169], v229 offset:17408
	ds_read_b128 v[170:173], v229 offset:18432
	ds_read_b128 v[174:177], v229 offset:19456
	ds_read_b128 v[178:181], v229 offset:20480
	ds_read_b128 v[182:185], v229 offset:21504
	ds_read_b128 v[186:189], v229 offset:22528
	ds_read_b128 v[200:203], v229 offset:23552
	global_load_lds_dwordx4 v8, s[42:43]
	s_add_i32 m0, s55, 0x2000
	s_add_u32 s56, s42, 0x20000
	s_addc_u32 s57, s43, 0
	s_add_i32 s18, s18, s20
	global_load_lds_dwordx4 v190, s[42:43]
	s_mov_b32 m0, s18
	s_nop 0
	global_load_lds_dwordx4 v8, s[56:57]
	s_add_i32 m0, s18, 0x2000
	s_nop 0
	global_load_lds_dwordx4 v190, s[56:57]
	s_mov_b32 m0, s21
	s_nop 0
	global_load_lds_dwordx4 v194, s[48:49]
	s_mov_b32 m0, s28
	s_nop 0
	global_load_lds_dwordx4 v192, s[48:49]
	s_waitcnt vmcnt(8)
	s_waitcnt lgkmcnt(0)
	s_barrier
	s_setprio 1
	s_waitcnt lgkmcnt(0)
	v_mfma_f32_16x16x32_bf16 v[62:65], v[118:121], v[162:165], v[62:65]
	v_mfma_f32_16x16x32_bf16 v[58:61], v[130:133], v[162:165], v[58:61]
	v_mfma_f32_16x16x32_bf16 v[46:49], v[118:121], v[170:173], v[46:49]
	v_mfma_f32_16x16x32_bf16 v[42:45], v[130:133], v[170:173], v[42:45]
	v_mfma_f32_16x16x32_bf16 v[30:33], v[118:121], v[178:181], v[30:33]
	v_mfma_f32_16x16x32_bf16 v[26:29], v[130:133], v[178:181], v[26:29]
	v_mfma_f32_16x16x32_bf16 v[14:17], v[118:121], v[186:189], v[14:17]
	v_mfma_f32_16x16x32_bf16 v[10:13], v[130:133], v[186:189], v[10:13]
	v_mfma_f32_16x16x32_bf16 v[62:65], v[126:129], v[166:169], v[62:65]
	v_mfma_f32_16x16x32_bf16 v[58:61], v[134:137], v[166:169], v[58:61]
	v_mfma_f32_16x16x32_bf16 v[46:49], v[126:129], v[174:177], v[46:49]
	v_mfma_f32_16x16x32_bf16 v[42:45], v[134:137], v[174:177], v[42:45]
	v_mfma_f32_16x16x32_bf16 v[30:33], v[126:129], v[182:185], v[30:33]
	v_mfma_f32_16x16x32_bf16 v[26:29], v[134:137], v[182:185], v[26:29]
	v_mfma_f32_16x16x32_bf16 v[14:17], v[126:129], v[200:203], v[14:17]
	v_mfma_f32_16x16x32_bf16 v[10:13], v[134:137], v[200:203], v[10:13]
	v_mfma_f32_16x16x32_bf16 v[54:57], v[138:141], v[162:165], v[54:57]
	v_mfma_f32_16x16x32_bf16 v[50:53], v[154:157], v[162:165], v[50:53]
	v_mfma_f32_16x16x32_bf16 v[38:41], v[138:141], v[170:173], v[38:41]
	v_mfma_f32_16x16x32_bf16 v[34:37], v[154:157], v[170:173], v[34:37]
	v_mfma_f32_16x16x32_bf16 v[22:25], v[138:141], v[178:181], v[22:25]
	v_mfma_f32_16x16x32_bf16 v[18:21], v[154:157], v[178:181], v[18:21]
	v_mfma_f32_16x16x32_bf16 v[4:7], v[138:141], v[186:189], v[4:7]
	v_mfma_f32_16x16x32_bf16 v[0:3], v[154:157], v[186:189], v[0:3]
	v_mfma_f32_16x16x32_bf16 v[54:57], v[150:153], v[166:169], v[54:57]
	v_mfma_f32_16x16x32_bf16 v[50:53], v[158:161], v[166:169], v[50:53]
	v_mfma_f32_16x16x32_bf16 v[38:41], v[150:153], v[174:177], v[38:41]
	v_mfma_f32_16x16x32_bf16 v[34:37], v[158:161], v[174:177], v[34:37]
	v_mfma_f32_16x16x32_bf16 v[22:25], v[150:153], v[182:185], v[22:25]
	v_mfma_f32_16x16x32_bf16 v[18:21], v[158:161], v[182:185], v[18:21]
	v_mfma_f32_16x16x32_bf16 v[4:7], v[150:153], v[200:203], v[4:7]
	v_mfma_f32_16x16x32_bf16 v[0:3], v[158:161], v[200:203], v[0:3]
	s_setprio 0
	s_barrier
; #define PG8_STAGE(bufoff, gbase, voff) do { _Pragma("unroll") for (int _i = 0; _i < 2; ++_i) \
;         __builtin_amdgcn_global_load_lds((const unsigned*)((const char*)(gbase) + (voff)[_i]), (PG8_LAS unsigned*)(lds + (bufoff) + ldsw + _i * 8192), 16, 0, 0); } while (0)
; #define PG8_LDA(dst, b, h) do { _Pragma("unroll") for (int m = 0; m < 4; ++m) _Pragma("unroll") for (int k = 0; k < 2; ++k) dst[m][k] = *(const PG8_LAS bf16x8*)(lds + PG8_SA(b, h) + aoff + m * 2048 + k * 1024); } while (0)
; #define PG8_LDB(dst, b, h) do { _Pragma("unroll") for (int n = 0; n < 2; ++n) _Pragma("unroll") for (int k = 0; k < 2; ++k) dst[n][k] = *(const PG8_LAS bf16x8*)(lds + PG8_SB(b, h) + boff + n * 2048 + k * 1024); } while (0)
; #define PG8_MMA(ai, bj, At, Bt) do { __builtin_amdgcn_s_setprio(1); _Pragma("unroll") for (int m = 0; m < 4; ++m) _Pragma("unroll") for (int n = 0; n < 2; ++n) _Pragma("unroll") for (int k = 0; k < 2; ++k) \
;         acc[ai][bj][m][n] = __builtin_amdgcn_mfma_f32_16x16x32_bf16(Bt[n][k], At[m][k], acc[ai][bj][m][n], 0, 0, 0); __builtin_amdgcn_s_setprio(0); } while (0)
; #define PG8_WAIT_V(n) asm volatile("s_waitcnt vmcnt(" #n ")" ::: "memory")
; #define PG8_WAIT_L(n) asm volatile("s_waitcnt lgkmcnt(" #n ")" ::: "memory")
; #define PG8_BAR __builtin_amdgcn_s_barrier()
; #define PG8_SCHED __builtin_amdgcn_sched_barrier(0)
; template <class Epi, class Sched, bool ALIGN_EPI = false, bool SP2 = false>
; __device__ __forceinline__ void gemm_phase(PG8_LAS unsigned char* lds, int tid_in, const Gemm g, const Sched& S, const Epi& E) {
;     ...
;             PG8_LDB(B0, 1, 0); PG8_LDB(B1, 1, 1); PG8_SCHED; PG8_LDA(At, 1, 0); PG8_STAGE(PG8_SA(0, 1), a2 + hstep, voffA);
;             PG8_WAIT_V(8); PG8_WAIT_L(0); PG8_BAR; PG8_MMA(0, 0, At, B0); PG8_MMA(0, 1, At, B1); PG8_BAR; PG8_SCHED;
	s_add_i32 s18, 0, 0x18000
	s_add_i32 s55, 0, 0x1c000
	v_add_u32_e32 v134, s18, v228
	v_add_u32_e32 v158, s55, v228
	ds_read_b128 v[118:121], v134
	ds_read_b128 v[126:129], v134 offset:1024
	ds_read_b128 v[130:133], v134 offset:2048
	ds_read_b128 v[134:137], v134 offset:3072
	ds_read_b128 v[138:141], v158
	ds_read_b128 v[150:153], v158 offset:1024
	ds_read_b128 v[154:157], v158 offset:2048
	ds_read_b128 v[158:161], v158 offset:3072
	s_add_u32 s48, s48, 0x20000
	s_addc_u32 s49, s49, 0
	s_mov_b32 m0, s29
	ds_read_b128 v[162:165], v229 offset:32768
	ds_read_b128 v[166:169], v229 offset:33792
	ds_read_b128 v[170:173], v229 offset:34816
	ds_read_b128 v[174:177], v229 offset:35840
	ds_read_b128 v[178:181], v229 offset:36864
	ds_read_b128 v[182:185], v229 offset:37888
	ds_read_b128 v[186:189], v229 offset:38912
	ds_read_b128 v[200:203], v229 offset:39936
	global_load_lds_dwordx4 v194, s[48:49]
	s_mov_b32 m0, s33
	s_nop 0
	global_load_lds_dwordx4 v192, s[48:49]
	s_waitcnt vmcnt(8)
	s_waitcnt lgkmcnt(0)
	s_barrier
	s_setprio 1
	s_waitcnt lgkmcnt(0)
	v_mfma_f32_16x16x32_bf16 v[146:149], v[118:121], v[162:165], v[146:149]
	v_mfma_f32_16x16x32_bf16 v[142:145], v[130:133], v[162:165], v[142:145]
	v_mfma_f32_16x16x32_bf16 v[110:113], v[118:121], v[170:173], v[110:113]
	v_mfma_f32_16x16x32_bf16 v[106:109], v[130:133], v[170:173], v[106:109]
	v_mfma_f32_16x16x32_bf16 v[94:97], v[118:121], v[178:181], v[94:97]
	v_mfma_f32_16x16x32_bf16 v[90:93], v[130:133], v[178:181], v[90:93]
	v_mfma_f32_16x16x32_bf16 v[78:81], v[118:121], v[186:189], v[78:81]
	v_mfma_f32_16x16x32_bf16 v[74:77], v[130:133], v[186:189], v[74:77]
	v_mfma_f32_16x16x32_bf16 v[146:149], v[126:129], v[166:169], v[146:149]
	v_mfma_f32_16x16x32_bf16 v[142:145], v[134:137], v[166:169], v[142:145]
	v_mfma_f32_16x16x32_bf16 v[110:113], v[126:129], v[174:177], v[110:113]
	v_mfma_f32_16x16x32_bf16 v[106:109], v[134:137], v[174:177], v[106:109]
	v_mfma_f32_16x16x32_bf16 v[94:97], v[126:129], v[182:185], v[94:97]
	v_mfma_f32_16x16x32_bf16 v[90:93], v[134:137], v[182:185], v[90:93]
	v_mfma_f32_16x16x32_bf16 v[78:81], v[126:129], v[200:203], v[78:81]
	v_mfma_f32_16x16x32_bf16 v[74:77], v[134:137], v[200:203], v[74:77]
	v_mfma_f32_16x16x32_bf16 v[122:125], v[138:141], v[162:165], v[122:125]
	v_mfma_f32_16x16x32_bf16 v[114:117], v[154:157], v[162:165], v[114:117]
	v_mfma_f32_16x16x32_bf16 v[102:105], v[138:141], v[170:173], v[102:105]
	v_mfma_f32_16x16x32_bf16 v[98:101], v[154:157], v[170:173], v[98:101]
	v_mfma_f32_16x16x32_bf16 v[86:89], v[138:141], v[178:181], v[86:89]
	v_mfma_f32_16x16x32_bf16 v[82:85], v[154:157], v[178:181], v[82:85]
	v_mfma_f32_16x16x32_bf16 v[70:73], v[138:141], v[186:189], v[70:73]
	v_mfma_f32_16x16x32_bf16 v[66:69], v[154:157], v[186:189], v[66:69]
	v_mfma_f32_16x16x32_bf16 v[122:125], v[150:153], v[166:169], v[122:125]
	v_mfma_f32_16x16x32_bf16 v[114:117], v[158:161], v[166:169], v[114:117]
	v_mfma_f32_16x16x32_bf16 v[102:105], v[150:153], v[174:177], v[102:105]
	v_mfma_f32_16x16x32_bf16 v[98:101], v[158:161], v[174:177], v[98:101]
	v_mfma_f32_16x16x32_bf16 v[86:89], v[150:153], v[182:185], v[86:89]
	v_mfma_f32_16x16x32_bf16 v[82:85], v[158:161], v[182:185], v[82:85]
	v_mfma_f32_16x16x32_bf16 v[70:73], v[150:153], v[200:203], v[70:73]
	v_mfma_f32_16x16x32_bf16 v[66:69], v[158:161], v[200:203], v[66:69]
	s_setprio 0
	s_barrier
; #define PG8_STAGE(bufoff, gbase, voff) do { _Pragma("unroll") for (int _i = 0; _i < 2; ++_i) \
;         __builtin_amdgcn_global_load_lds((const unsigned*)((const char*)(gbase) + (voff)[_i]), (PG8_LAS unsigned*)(lds + (bufoff) + ldsw + _i * 8192), 16, 0, 0); } while (0)
; #define PG8_LDA(dst, b, h) do { _Pragma("unroll") for (int m = 0; m < 4; ++m) _Pragma("unroll") for (int k = 0; k < 2; ++k) dst[m][k] = *(const PG8_LAS bf16x8*)(lds + PG8_SA(b, h) + aoff + m * 2048 + k * 1024); } while (0)
; #define PG8_MMA(ai, bj, At, Bt) do { __builtin_amdgcn_s_setprio(1); _Pragma("unroll") for (int m = 0; m < 4; ++m) _Pragma("unroll") for (int n = 0; n < 2; ++n) _Pragma("unroll") for (int k = 0; k < 2; ++k) \
;         acc[ai][bj][m][n] = __builtin_amdgcn_mfma_f32_16x16x32_bf16(Bt[n][k], At[m][k], acc[ai][bj][m][n], 0, 0, 0); __builtin_amdgcn_s_setprio(0); } while (0)
; #define PG8_WAIT_V(n) asm volatile("s_waitcnt vmcnt(" #n ")" ::: "memory")
; #define PG8_WAIT_L(n) asm volatile("s_waitcnt lgkmcnt(" #n ")" ::: "memory")
; #define PG8_BAR __builtin_amdgcn_s_barrier()
; #define PG8_SCHED __builtin_amdgcn_sched_barrier(0)
; template <class Epi, class Sched, bool ALIGN_EPI = false, bool SP2 = false>
; __device__ __forceinline__ void gemm_phase(PG8_LAS unsigned char* lds, int tid_in, const Gemm g, const Sched& S, const Epi& E) {
;     ...
;         for (int t = 0; t < nt; t += 2) {
;     ...
;             PG8_LDA(At, 1, 1); PG8_STAGE(PG8_SB(1, 0), b3, voffB); PG8_STAGE(PG8_SB(1, 1), b3 + hstep, voffB); PG8_STAGE(PG8_SA(1, 0), a3, voffA);
;             PG8_WAIT_V(8); PG8_WAIT_L(0); PG8_BAR; PG8_MMA(1, 0, At, B0); PG8_MMA(1, 1, At, B1); PG8_BAR; PG8_SCHED;
	s_add_i32 s18, s18, s20
	s_mov_b32 m0, s18
	ds_read_b128 v[162:165], v229 offset:49152
	ds_read_b128 v[166:169], v229 offset:50176
	ds_read_b128 v[170:173], v229 offset:51200
	ds_read_b128 v[174:177], v229 offset:52224
	ds_read_b128 v[178:181], v229 offset:53248
	ds_read_b128 v[182:185], v229 offset:54272
	ds_read_b128 v[186:189], v229 offset:55296
	ds_read_b128 v[200:203], v229 offset:56320
	s_add_u32 s42, s42, 0x80
	s_addc_u32 s43, s43, 0
	global_load_lds_dwordx4 v8, s[42:43]
	s_sub_u32 s42, s42, 0x80
	s_subb_u32 s43, s43, 0
	s_add_i32 m0, s18, 0x2000
	s_add_u32 s42, s42, 0x20080
	s_addc_u32 s43, s43, 0
	s_add_i32 s18, s55, s20
	s_sub_u32 s42, s42, 0x20000
	s_subb_u32 s43, s43, 0
	global_load_lds_dwordx4 v190, s[42:43]
	s_add_u32 s42, s42, 0x20000
	s_addc_u32 s43, s43, 0
	s_mov_b32 m0, s18
	s_nop 0
	global_load_lds_dwordx4 v8, s[42:43]
	s_add_i32 m0, s18, 0x2000
	s_nop 0
	global_load_lds_dwordx4 v190, s[42:43]
	s_mov_b32 m0, s45
	s_nop 0
	s_sub_u32 s48, s48, 0x1ff80
	s_subb_u32 s49, s49, 0
	global_load_lds_dwordx4 v194, s[48:49]
	s_add_u32 s48, s48, 0x1ff80
	s_addc_u32 s49, s49, 0
	s_mov_b32 m0, s46
	s_nop 0
	s_sub_u32 s48, s48, 0x1ff80
	s_subb_u32 s49, s49, 0
	global_load_lds_dwordx4 v192, s[48:49]
	s_add_u32 s48, s48, 0x1ff80
	s_addc_u32 s49, s49, 0
	s_waitcnt vmcnt(8)
	s_waitcnt lgkmcnt(0)
	s_barrier
	s_setprio 1
	s_waitcnt lgkmcnt(0)
	v_mfma_f32_16x16x32_bf16 v[62:65], v[118:121], v[162:165], v[62:65]
	v_mfma_f32_16x16x32_bf16 v[58:61], v[130:133], v[162:165], v[58:61]
	v_mfma_f32_16x16x32_bf16 v[46:49], v[118:121], v[170:173], v[46:49]
	v_mfma_f32_16x16x32_bf16 v[42:45], v[130:133], v[170:173], v[42:45]
	v_mfma_f32_16x16x32_bf16 v[30:33], v[118:121], v[178:181], v[30:33]
	v_mfma_f32_16x16x32_bf16 v[26:29], v[130:133], v[178:181], v[26:29]
	v_mfma_f32_16x16x32_bf16 v[14:17], v[118:121], v[186:189], v[14:17]
	v_mfma_f32_16x16x32_bf16 v[10:13], v[130:133], v[186:189], v[10:13]
	v_mfma_f32_16x16x32_bf16 v[62:65], v[126:129], v[166:169], v[62:65]
	v_mfma_f32_16x16x32_bf16 v[58:61], v[134:137], v[166:169], v[58:61]
	v_mfma_f32_16x16x32_bf16 v[46:49], v[126:129], v[174:177], v[46:49]
	v_mfma_f32_16x16x32_bf16 v[42:45], v[134:137], v[174:177], v[42:45]
	v_mfma_f32_16x16x32_bf16 v[30:33], v[126:129], v[182:185], v[30:33]
	v_mfma_f32_16x16x32_bf16 v[26:29], v[134:137], v[182:185], v[26:29]
	v_mfma_f32_16x16x32_bf16 v[14:17], v[126:129], v[200:203], v[14:17]
	v_mfma_f32_16x16x32_bf16 v[10:13], v[134:137], v[200:203], v[10:13]
	v_mfma_f32_16x16x32_bf16 v[54:57], v[138:141], v[162:165], v[54:57]
	v_mfma_f32_16x16x32_bf16 v[50:53], v[154:157], v[162:165], v[50:53]
	v_mfma_f32_16x16x32_bf16 v[38:41], v[138:141], v[170:173], v[38:41]
	v_mfma_f32_16x16x32_bf16 v[34:37], v[154:157], v[170:173], v[34:37]
	v_mfma_f32_16x16x32_bf16 v[22:25], v[138:141], v[178:181], v[22:25]
	v_mfma_f32_16x16x32_bf16 v[18:21], v[154:157], v[178:181], v[18:21]
	v_mfma_f32_16x16x32_bf16 v[4:7], v[138:141], v[186:189], v[4:7]
	v_mfma_f32_16x16x32_bf16 v[0:3], v[154:157], v[186:189], v[0:3]
	v_mfma_f32_16x16x32_bf16 v[54:57], v[150:153], v[166:169], v[54:57]
	v_mfma_f32_16x16x32_bf16 v[50:53], v[158:161], v[166:169], v[50:53]
	v_mfma_f32_16x16x32_bf16 v[38:41], v[150:153], v[174:177], v[38:41]
	v_mfma_f32_16x16x32_bf16 v[34:37], v[158:161], v[174:177], v[34:37]
	v_mfma_f32_16x16x32_bf16 v[22:25], v[150:153], v[182:185], v[22:25]
	v_mfma_f32_16x16x32_bf16 v[18:21], v[158:161], v[182:185], v[18:21]
	v_mfma_f32_16x16x32_bf16 v[4:7], v[150:153], v[200:203], v[4:7]
	v_mfma_f32_16x16x32_bf16 v[0:3], v[158:161], v[200:203], v[0:3]
	s_setprio 0
	s_barrier
	s_add_i32 s37, s37, 2
	s_add_u32 s34, s34, 0x100
	s_addc_u32 s35, s35, 0
	s_add_u32 s39, s39, 0x100
	s_addc_u32 s36, s36, 0
	s_cmp_gt_u32 s37, 5
	s_cbranch_scc0 .LBB0_592
	s_and_b64 vcc, exec, s[10:11]
	s_cbranch_vccz .LBB0_595
	s_barrier

; #define PG8_STAGE(bufoff, gbase, voff) do { _Pragma("unroll") for (int _i = 0; _i < 2; ++_i) \
;         __builtin_amdgcn_global_load_lds((const unsigned*)((const char*)(gbase) + (voff)[_i]), (PG8_LAS unsigned*)(lds + (bufoff) + ldsw + _i * 8192), 16, 0, 0); } while (0)
; #define PG8_LDA(dst, b, h) do { _Pragma("unroll") for (int m = 0; m < 4; ++m) _Pragma("unroll") for (int k = 0; k < 2; ++k) dst[m][k] = *(const PG8_LAS bf16x8*)(lds + PG8_SA(b, h) + aoff + m * 2048 + k * 1024); } while (0)
; #define PG8_LDB(dst, b, h) do { _Pragma("unroll") for (int n = 0; n < 2; ++n) _Pragma("unroll") for (int k = 0; k < 2; ++k) dst[n][k] = *(const PG8_LAS bf16x8*)(lds + PG8_SB(b, h) + boff + n * 2048 + k * 1024); } while (0)
; #define PG8_MMA(ai, bj, At, Bt) do { __builtin_amdgcn_s_setprio(1); _Pragma("unroll") for (int m = 0; m < 4; ++m) _Pragma("unroll") for (int n = 0; n < 2; ++n) _Pragma("unroll") for (int k = 0; k < 2; ++k) \
;         acc[ai][bj][m][n] = __builtin_amdgcn_mfma_f32_16x16x32_bf16(Bt[n][k], At[m][k], acc[ai][bj][m][n], 0, 0, 0); __builtin_amdgcn_s_setprio(0); } while (0)
; #define PG8_WAIT_V(n) asm volatile("s_waitcnt vmcnt(" #n ")" ::: "memory")
; #define PG8_WAIT_L(n) asm volatile("s_waitcnt lgkmcnt(" #n ")" ::: "memory")
; #define PG8_BAR __builtin_amdgcn_s_barrier()
; #define PG8_SCHED __builtin_amdgcn_sched_barrier(0)
; template <class Epi, class Sched, bool ALIGN_EPI = false, bool SP2 = false>
; __device__ __forceinline__ void gemm_phase(PG8_LAS unsigned char* lds, int tid_in, const Gemm g, const Sched& S, const Epi& E) {
;     ...
;             PG8_LDB(B0, 0, 0); PG8_LDB(B1, 0, 1); PG8_SCHED; PG8_LDA(At, 0, 0); PG8_STAGE(PG8_SA(1, 1), a1 + hstep, voffA);
;             PG8_WAIT_V(8); PG8_WAIT_L(0); PG8_BAR; PG8_MMA(0, 0, At, B0); PG8_MMA(0, 1, At, B1); PG8_BAR; PG8_SCHED;
;             PG8_LDA(At, 0, 1); PG8_STAGE(PG8_SB(0, 0), b2, voffB); PG8_STAGE(PG8_SB(0, 1), b2 + hstep, voffB); PG8_STAGE(PG8_SA(0, 0), a2, voffA);
;             PG8_WAIT_V(8); PG8_WAIT_L(0); PG8_BAR; PG8_MMA(1, 0, At, B0); PG8_MMA(1, 1, At, B1); PG8_BAR; PG8_SCHED;
.LBB0_835:
	s_add_u32 s18, s34, 0xfffc0080
	s_addc_u32 s42, s35, -1
	s_add_i32 s55, 0, 0x10000
	s_cmp_eq_u32 s37, 12
	s_cselect_b32 s49, s17, s42
	s_cselect_b32 s48, s53, s18
	s_cselect_b32 s43, s15, s36
	s_cselect_b32 s42, s38, s39
	s_add_i32 s18, 0, 0x14000
	v_add_u32_e32 v118, s55, v158
	v_add_u32_e32 v156, s18, v158
	ds_read_b128 v[106:109], v118
	ds_read_b128 v[110:113], v118 offset:1024
	ds_read_b128 v[114:117], v118 offset:2048
	ds_read_b128 v[118:121], v118 offset:3072
	ds_read_b128 v[160:163], v156
	ds_read_b128 v[164:167], v156 offset:1024
	ds_read_b128 v[168:171], v156 offset:2048
	ds_read_b128 v[172:175], v156 offset:3072
	s_add_i32 m0, s0, 0xc000
	ds_read_b128 v[176:179], v159
	ds_read_b128 v[180:183], v159 offset:1024
	ds_read_b128 v[184:187], v159 offset:2048
	ds_read_b128 v[188:191], v159 offset:3072
	ds_read_b128 v[192:195], v159 offset:4096
	ds_read_b128 v[196:199], v159 offset:5120
	ds_read_b128 v[200:203], v159 offset:6144
	ds_read_b128 v[210:213], v159 offset:7168
	global_load_lds_dwordx4 v152, s[34:35]
	s_add_i32 m0, s0, 0xe000
	s_nop 0
	global_load_lds_dwordx4 v154, s[34:35]
	s_waitcnt vmcnt(8)
	s_waitcnt lgkmcnt(0)
	s_barrier
	s_setprio 1
	s_waitcnt lgkmcnt(0)
	v_mfma_f32_16x16x32_bf16 v[142:145], v[106:109], v[176:179], v[142:145]
	v_mfma_f32_16x16x32_bf16 v[138:141], v[114:117], v[176:179], v[138:141]
	v_mfma_f32_16x16x32_bf16 v[126:129], v[106:109], v[184:187], v[126:129]
	v_mfma_f32_16x16x32_bf16 v[122:125], v[114:117], v[184:187], v[122:125]
	v_mfma_f32_16x16x32_bf16 v[94:97], v[106:109], v[192:195], v[94:97]
	v_mfma_f32_16x16x32_bf16 v[90:93], v[114:117], v[192:195], v[90:93]
	v_mfma_f32_16x16x32_bf16 v[78:81], v[106:109], v[200:203], v[78:81]
	v_mfma_f32_16x16x32_bf16 v[74:77], v[114:117], v[200:203], v[74:77]
	v_mfma_f32_16x16x32_bf16 v[142:145], v[110:113], v[180:183], v[142:145]
	v_mfma_f32_16x16x32_bf16 v[138:141], v[118:121], v[180:183], v[138:141]
	v_mfma_f32_16x16x32_bf16 v[126:129], v[110:113], v[188:191], v[126:129]
	v_mfma_f32_16x16x32_bf16 v[122:125], v[118:121], v[188:191], v[122:125]
	v_mfma_f32_16x16x32_bf16 v[94:97], v[110:113], v[196:199], v[94:97]
	v_mfma_f32_16x16x32_bf16 v[90:93], v[118:121], v[196:199], v[90:93]
	v_mfma_f32_16x16x32_bf16 v[78:81], v[110:113], v[210:213], v[78:81]
	v_mfma_f32_16x16x32_bf16 v[74:77], v[118:121], v[210:213], v[74:77]
	v_mfma_f32_16x16x32_bf16 v[134:137], v[160:163], v[176:179], v[134:137]
	v_mfma_f32_16x16x32_bf16 v[130:133], v[168:171], v[176:179], v[130:133]
	v_mfma_f32_16x16x32_bf16 v[102:105], v[160:163], v[184:187], v[102:105]
	v_mfma_f32_16x16x32_bf16 v[98:101], v[168:171], v[184:187], v[98:101]
	v_mfma_f32_16x16x32_bf16 v[86:89], v[160:163], v[192:195], v[86:89]
	v_mfma_f32_16x16x32_bf16 v[82:85], v[168:171], v[192:195], v[82:85]
	v_mfma_f32_16x16x32_bf16 v[70:73], v[160:163], v[200:203], v[70:73]
	v_mfma_f32_16x16x32_bf16 v[66:69], v[168:171], v[200:203], v[66:69]
	v_mfma_f32_16x16x32_bf16 v[134:137], v[164:167], v[180:183], v[134:137]
	v_mfma_f32_16x16x32_bf16 v[130:133], v[172:175], v[180:183], v[130:133]
	v_mfma_f32_16x16x32_bf16 v[102:105], v[164:167], v[188:191], v[102:105]
	v_mfma_f32_16x16x32_bf16 v[98:101], v[172:175], v[188:191], v[98:101]
	v_mfma_f32_16x16x32_bf16 v[86:89], v[164:167], v[196:199], v[86:89]
	v_mfma_f32_16x16x32_bf16 v[82:85], v[172:175], v[196:199], v[82:85]
	v_mfma_f32_16x16x32_bf16 v[70:73], v[164:167], v[210:213], v[70:73]
	v_mfma_f32_16x16x32_bf16 v[66:69], v[172:175], v[210:213], v[66:69]
	s_setprio 0
	s_barrier
	s_add_i32 s55, s55, s44
	s_mov_b32 m0, s55
	ds_read_b128 v[176:179], v159 offset:16384
	ds_read_b128 v[180:183], v159 offset:17408
	ds_read_b128 v[184:187], v159 offset:18432
	ds_read_b128 v[188:191], v159 offset:19456
	ds_read_b128 v[192:195], v159 offset:20480
	ds_read_b128 v[196:199], v159 offset:21504
	ds_read_b128 v[200:203], v159 offset:22528
	ds_read_b128 v[210:213], v159 offset:23552
	global_load_lds_dwordx4 v8, s[42:43]
	s_add_i32 m0, s55, 0x2000
	s_add_u32 s56, s42, 0x40000
	s_addc_u32 s57, s43, 0
	s_add_i32 s18, s18, s44
	global_load_lds_dwordx4 v146, s[42:43]
	s_mov_b32 m0, s18
	s_nop 0
	global_load_lds_dwordx4 v8, s[56:57]
	s_add_i32 m0, s18, 0x2000
	s_nop 0
	global_load_lds_dwordx4 v146, s[56:57]
	s_mov_b32 m0, s0
	s_nop 0
	global_load_lds_dwordx4 v150, s[48:49]
	s_mov_b32 m0, s1
	s_nop 0
	global_load_lds_dwordx4 v148, s[48:49]
	s_waitcnt vmcnt(8)
	s_waitcnt lgkmcnt(0)
	s_barrier
	s_setprio 1
	s_waitcnt lgkmcnt(0)
	v_mfma_f32_16x16x32_bf16 v[62:65], v[106:109], v[176:179], v[62:65]
	v_mfma_f32_16x16x32_bf16 v[58:61], v[114:117], v[176:179], v[58:61]
	v_mfma_f32_16x16x32_bf16 v[46:49], v[106:109], v[184:187], v[46:49]
	v_mfma_f32_16x16x32_bf16 v[42:45], v[114:117], v[184:187], v[42:45]
	v_mfma_f32_16x16x32_bf16 v[30:33], v[106:109], v[192:195], v[30:33]
	v_mfma_f32_16x16x32_bf16 v[26:29], v[114:117], v[192:195], v[26:29]
	v_mfma_f32_16x16x32_bf16 v[14:17], v[106:109], v[200:203], v[14:17]
	v_mfma_f32_16x16x32_bf16 v[10:13], v[114:117], v[200:203], v[10:13]
	v_mfma_f32_16x16x32_bf16 v[62:65], v[110:113], v[180:183], v[62:65]
	v_mfma_f32_16x16x32_bf16 v[58:61], v[118:121], v[180:183], v[58:61]
	v_mfma_f32_16x16x32_bf16 v[46:49], v[110:113], v[188:191], v[46:49]
	v_mfma_f32_16x16x32_bf16 v[42:45], v[118:121], v[188:191], v[42:45]
	v_mfma_f32_16x16x32_bf16 v[30:33], v[110:113], v[196:199], v[30:33]
	v_mfma_f32_16x16x32_bf16 v[26:29], v[118:121], v[196:199], v[26:29]
	v_mfma_f32_16x16x32_bf16 v[14:17], v[110:113], v[210:213], v[14:17]
	v_mfma_f32_16x16x32_bf16 v[10:13], v[118:121], v[210:213], v[10:13]
	v_mfma_f32_16x16x32_bf16 v[54:57], v[160:163], v[176:179], v[54:57]
	v_mfma_f32_16x16x32_bf16 v[50:53], v[168:171], v[176:179], v[50:53]
	v_mfma_f32_16x16x32_bf16 v[38:41], v[160:163], v[184:187], v[38:41]
	v_mfma_f32_16x16x32_bf16 v[34:37], v[168:171], v[184:187], v[34:37]
	v_mfma_f32_16x16x32_bf16 v[22:25], v[160:163], v[192:195], v[22:25]
	v_mfma_f32_16x16x32_bf16 v[18:21], v[168:171], v[192:195], v[18:21]
	v_mfma_f32_16x16x32_bf16 v[4:7], v[160:163], v[200:203], v[4:7]
	v_mfma_f32_16x16x32_bf16 v[0:3], v[168:171], v[200:203], v[0:3]
	v_mfma_f32_16x16x32_bf16 v[54:57], v[164:167], v[180:183], v[54:57]
	v_mfma_f32_16x16x32_bf16 v[50:53], v[172:175], v[180:183], v[50:53]
	v_mfma_f32_16x16x32_bf16 v[38:41], v[164:167], v[188:191], v[38:41]
	v_mfma_f32_16x16x32_bf16 v[34:37], v[172:175], v[188:191], v[34:37]
	v_mfma_f32_16x16x32_bf16 v[22:25], v[164:167], v[196:199], v[22:25]
	v_mfma_f32_16x16x32_bf16 v[18:21], v[172:175], v[196:199], v[18:21]
	v_mfma_f32_16x16x32_bf16 v[4:7], v[164:167], v[210:213], v[4:7]
	v_mfma_f32_16x16x32_bf16 v[0:3], v[172:175], v[210:213], v[0:3]
	s_setprio 0
	s_barrier
; #define PG8_STAGE(bufoff, gbase, voff) do { _Pragma("unroll") for (int _i = 0; _i < 2; ++_i) \
;         __builtin_amdgcn_global_load_lds((const unsigned*)((const char*)(gbase) + (voff)[_i]), (PG8_LAS unsigned*)(lds + (bufoff) + ldsw + _i * 8192), 16, 0, 0); } while (0)
; #define PG8_LDA(dst, b, h) do { _Pragma("unroll") for (int m = 0; m < 4; ++m) _Pragma("unroll") for (int k = 0; k < 2; ++k) dst[m][k] = *(const PG8_LAS bf16x8*)(lds + PG8_SA(b, h) + aoff + m * 2048 + k * 1024); } while (0)
; #define PG8_LDB(dst, b, h) do { _Pragma("unroll") for (int n = 0; n < 2; ++n) _Pragma("unroll") for (int k = 0; k < 2; ++k) dst[n][k] = *(const PG8_LAS bf16x8*)(lds + PG8_SB(b, h) + boff + n * 2048 + k * 1024); } while (0)
; #define PG8_MMA(ai, bj, At, Bt) do { __builtin_amdgcn_s_setprio(1); _Pragma("unroll") for (int m = 0; m < 4; ++m) _Pragma("unroll") for (int n = 0; n < 2; ++n) _Pragma("unroll") for (int k = 0; k < 2; ++k) \
;         acc[ai][bj][m][n] = __builtin_amdgcn_mfma_f32_16x16x32_bf16(Bt[n][k], At[m][k], acc[ai][bj][m][n], 0, 0, 0); __builtin_amdgcn_s_setprio(0); } while (0)
; #define PG8_WAIT_V(n) asm volatile("s_waitcnt vmcnt(" #n ")" ::: "memory")
; #define PG8_WAIT_L(n) asm volatile("s_waitcnt lgkmcnt(" #n ")" ::: "memory")
; #define PG8_BAR __builtin_amdgcn_s_barrier()
; #define PG8_SCHED __builtin_amdgcn_sched_barrier(0)
; template <class Epi, class Sched, bool ALIGN_EPI = false, bool SP2 = false>
; __device__ __forceinline__ void gemm_phase(PG8_LAS unsigned char* lds, int tid_in, const Gemm g, const Sched& S, const Epi& E) {
;     ...
;             PG8_LDB(B0, 1, 0); PG8_LDB(B1, 1, 1); PG8_SCHED; PG8_LDA(At, 1, 0); PG8_STAGE(PG8_SA(0, 1), a2 + hstep, voffA);
;             PG8_WAIT_V(8); PG8_WAIT_L(0); PG8_BAR; PG8_MMA(0, 0, At, B0); PG8_MMA(0, 1, At, B1); PG8_BAR; PG8_SCHED;
	s_add_i32 s18, 0, 0x18000
	s_add_i32 s55, 0, 0x1c000
	v_add_u32_e32 v118, s18, v158
	v_add_u32_e32 v172, s55, v158
	ds_read_b128 v[106:109], v118
	ds_read_b128 v[110:113], v118 offset:1024
	ds_read_b128 v[114:117], v118 offset:2048
	ds_read_b128 v[118:121], v118 offset:3072
	ds_read_b128 v[160:163], v172
	ds_read_b128 v[164:167], v172 offset:1024
	ds_read_b128 v[168:171], v172 offset:2048
	ds_read_b128 v[172:175], v172 offset:3072
	s_add_u32 s48, s48, 0x40000
	s_addc_u32 s49, s49, 0
	s_mov_b32 m0, s20
	ds_read_b128 v[176:179], v159 offset:32768
	ds_read_b128 v[180:183], v159 offset:33792
	ds_read_b128 v[184:187], v159 offset:34816
	ds_read_b128 v[188:191], v159 offset:35840
	ds_read_b128 v[192:195], v159 offset:36864
	ds_read_b128 v[196:199], v159 offset:37888
	ds_read_b128 v[200:203], v159 offset:38912
	ds_read_b128 v[210:213], v159 offset:39936
	global_load_lds_dwordx4 v150, s[48:49]
	s_mov_b32 m0, s21
	s_nop 0
	global_load_lds_dwordx4 v148, s[48:49]
	s_waitcnt vmcnt(8)
	s_waitcnt lgkmcnt(0)
	s_barrier
	s_setprio 1
	s_waitcnt lgkmcnt(0)
	v_mfma_f32_16x16x32_bf16 v[142:145], v[106:109], v[176:179], v[142:145]
	v_mfma_f32_16x16x32_bf16 v[138:141], v[114:117], v[176:179], v[138:141]
	v_mfma_f32_16x16x32_bf16 v[126:129], v[106:109], v[184:187], v[126:129]
	v_mfma_f32_16x16x32_bf16 v[122:125], v[114:117], v[184:187], v[122:125]
	v_mfma_f32_16x16x32_bf16 v[94:97], v[106:109], v[192:195], v[94:97]
	v_mfma_f32_16x16x32_bf16 v[90:93], v[114:117], v[192:195], v[90:93]
	v_mfma_f32_16x16x32_bf16 v[78:81], v[106:109], v[200:203], v[78:81]
	v_mfma_f32_16x16x32_bf16 v[74:77], v[114:117], v[200:203], v[74:77]
	v_mfma_f32_16x16x32_bf16 v[142:145], v[110:113], v[180:183], v[142:145]
	v_mfma_f32_16x16x32_bf16 v[138:141], v[118:121], v[180:183], v[138:141]
	v_mfma_f32_16x16x32_bf16 v[126:129], v[110:113], v[188:191], v[126:129]
	v_mfma_f32_16x16x32_bf16 v[122:125], v[118:121], v[188:191], v[122:125]
	v_mfma_f32_16x16x32_bf16 v[94:97], v[110:113], v[196:199], v[94:97]
	v_mfma_f32_16x16x32_bf16 v[90:93], v[118:121], v[196:199], v[90:93]
	v_mfma_f32_16x16x32_bf16 v[78:81], v[110:113], v[210:213], v[78:81]
	v_mfma_f32_16x16x32_bf16 v[74:77], v[118:121], v[210:213], v[74:77]
	v_mfma_f32_16x16x32_bf16 v[134:137], v[160:163], v[176:179], v[134:137]
	v_mfma_f32_16x16x32_bf16 v[130:133], v[168:171], v[176:179], v[130:133]
	v_mfma_f32_16x16x32_bf16 v[102:105], v[160:163], v[184:187], v[102:105]
	v_mfma_f32_16x16x32_bf16 v[98:101], v[168:171], v[184:187], v[98:101]
	v_mfma_f32_16x16x32_bf16 v[86:89], v[160:163], v[192:195], v[86:89]
	v_mfma_f32_16x16x32_bf16 v[82:85], v[168:171], v[192:195], v[82:85]
	v_mfma_f32_16x16x32_bf16 v[70:73], v[160:163], v[200:203], v[70:73]
	v_mfma_f32_16x16x32_bf16 v[66:69], v[168:171], v[200:203], v[66:69]
	v_mfma_f32_16x16x32_bf16 v[134:137], v[164:167], v[180:183], v[134:137]
	v_mfma_f32_16x16x32_bf16 v[130:133], v[172:175], v[180:183], v[130:133]
	v_mfma_f32_16x16x32_bf16 v[102:105], v[164:167], v[188:191], v[102:105]
	v_mfma_f32_16x16x32_bf16 v[98:101], v[172:175], v[188:191], v[98:101]
	v_mfma_f32_16x16x32_bf16 v[86:89], v[164:167], v[196:199], v[86:89]
	v_mfma_f32_16x16x32_bf16 v[82:85], v[172:175], v[196:199], v[82:85]
	v_mfma_f32_16x16x32_bf16 v[70:73], v[164:167], v[210:213], v[70:73]
	v_mfma_f32_16x16x32_bf16 v[66:69], v[172:175], v[210:213], v[66:69]
	s_setprio 0
	s_barrier
; #define PG8_STAGE(bufoff, gbase, voff) do { _Pragma("unroll") for (int _i = 0; _i < 2; ++_i) \
;         __builtin_amdgcn_global_load_lds((const unsigned*)((const char*)(gbase) + (voff)[_i]), (PG8_LAS unsigned*)(lds + (bufoff) + ldsw + _i * 8192), 16, 0, 0); } while (0)
; #define PG8_LDA(dst, b, h) do { _Pragma("unroll") for (int m = 0; m < 4; ++m) _Pragma("unroll") for (int k = 0; k < 2; ++k) dst[m][k] = *(const PG8_LAS bf16x8*)(lds + PG8_SA(b, h) + aoff + m * 2048 + k * 1024); } while (0)
; #define PG8_MMA(ai, bj, At, Bt) do { __builtin_amdgcn_s_setprio(1); _Pragma("unroll") for (int m = 0; m < 4; ++m) _Pragma("unroll") for (int n = 0; n < 2; ++n) _Pragma("unroll") for (int k = 0; k < 2; ++k) \
;         acc[ai][bj][m][n] = __builtin_amdgcn_mfma_f32_16x16x32_bf16(Bt[n][k], At[m][k], acc[ai][bj][m][n], 0, 0, 0); __builtin_amdgcn_s_setprio(0); } while (0)
; #define PG8_WAIT_V(n) asm volatile("s_waitcnt vmcnt(" #n ")" ::: "memory")
; #define PG8_WAIT_L(n) asm volatile("s_waitcnt lgkmcnt(" #n ")" ::: "memory")
; #define PG8_BAR __builtin_amdgcn_s_barrier()
; #define PG8_SCHED __builtin_amdgcn_sched_barrier(0)
; template <class Epi, class Sched, bool ALIGN_EPI = false, bool SP2 = false>
; __device__ __forceinline__ void gemm_phase(PG8_LAS unsigned char* lds, int tid_in, const Gemm g, const Sched& S, const Epi& E) {
;     ...
;         for (int t = 0; t < nt; t += 2) {
;     ...
;             PG8_LDA(At, 1, 1); PG8_STAGE(PG8_SB(1, 0), b3, voffB); PG8_STAGE(PG8_SB(1, 1), b3 + hstep, voffB); PG8_STAGE(PG8_SA(1, 0), a3, voffA);
;             PG8_WAIT_V(8); PG8_WAIT_L(0); PG8_BAR; PG8_MMA(1, 0, At, B0); PG8_MMA(1, 1, At, B1); PG8_BAR; PG8_SCHED;
	s_add_i32 s18, s18, s44
	s_mov_b32 m0, s18
	ds_read_b128 v[176:179], v159 offset:49152
	ds_read_b128 v[180:183], v159 offset:50176
	ds_read_b128 v[184:187], v159 offset:51200
	ds_read_b128 v[188:191], v159 offset:52224
	ds_read_b128 v[192:195], v159 offset:53248
	ds_read_b128 v[196:199], v159 offset:54272
	ds_read_b128 v[200:203], v159 offset:55296
	ds_read_b128 v[210:213], v159 offset:56320
	s_add_u32 s42, s42, 0x80
	s_addc_u32 s43, s43, 0
	global_load_lds_dwordx4 v8, s[42:43]
	s_sub_u32 s42, s42, 0x80
	s_subb_u32 s43, s43, 0
	s_add_i32 m0, s18, 0x2000
	s_add_u32 s42, s42, 0x40080
	s_addc_u32 s43, s43, 0
	s_add_i32 s18, s55, s44
	s_sub_u32 s42, s42, 0x40000
	s_subb_u32 s43, s43, 0
	global_load_lds_dwordx4 v146, s[42:43]
	s_add_u32 s42, s42, 0x40000
	s_addc_u32 s43, s43, 0
	s_mov_b32 m0, s18
	s_nop 0
	global_load_lds_dwordx4 v8, s[42:43]
	s_add_i32 m0, s18, 0x2000
	s_nop 0
	global_load_lds_dwordx4 v146, s[42:43]
	s_mov_b32 m0, s29
	s_nop 0
	s_sub_u32 s48, s48, 0x3ff80
	s_subb_u32 s49, s49, 0
	global_load_lds_dwordx4 v150, s[48:49]
	s_add_u32 s48, s48, 0x3ff80
	s_addc_u32 s49, s49, 0
	s_mov_b32 m0, s46
	s_nop 0
	s_sub_u32 s48, s48, 0x3ff80
	s_subb_u32 s49, s49, 0
	global_load_lds_dwordx4 v148, s[48:49]
	s_add_u32 s48, s48, 0x3ff80
	s_addc_u32 s49, s49, 0
	s_waitcnt vmcnt(8)
	s_waitcnt lgkmcnt(0)
	s_barrier
	s_setprio 1
	s_waitcnt lgkmcnt(0)
	v_mfma_f32_16x16x32_bf16 v[62:65], v[106:109], v[176:179], v[62:65]
	v_mfma_f32_16x16x32_bf16 v[58:61], v[114:117], v[176:179], v[58:61]
	v_mfma_f32_16x16x32_bf16 v[46:49], v[106:109], v[184:187], v[46:49]
	v_mfma_f32_16x16x32_bf16 v[42:45], v[114:117], v[184:187], v[42:45]
	v_mfma_f32_16x16x32_bf16 v[30:33], v[106:109], v[192:195], v[30:33]
	v_mfma_f32_16x16x32_bf16 v[26:29], v[114:117], v[192:195], v[26:29]
	v_mfma_f32_16x16x32_bf16 v[14:17], v[106:109], v[200:203], v[14:17]
	v_mfma_f32_16x16x32_bf16 v[10:13], v[114:117], v[200:203], v[10:13]
	v_mfma_f32_16x16x32_bf16 v[62:65], v[110:113], v[180:183], v[62:65]
	v_mfma_f32_16x16x32_bf16 v[58:61], v[118:121], v[180:183], v[58:61]
	v_mfma_f32_16x16x32_bf16 v[46:49], v[110:113], v[188:191], v[46:49]
	v_mfma_f32_16x16x32_bf16 v[42:45], v[118:121], v[188:191], v[42:45]
	v_mfma_f32_16x16x32_bf16 v[30:33], v[110:113], v[196:199], v[30:33]
	v_mfma_f32_16x16x32_bf16 v[26:29], v[118:121], v[196:199], v[26:29]
	v_mfma_f32_16x16x32_bf16 v[14:17], v[110:113], v[210:213], v[14:17]
	v_mfma_f32_16x16x32_bf16 v[10:13], v[118:121], v[210:213], v[10:13]
	v_mfma_f32_16x16x32_bf16 v[54:57], v[160:163], v[176:179], v[54:57]
	v_mfma_f32_16x16x32_bf16 v[50:53], v[168:171], v[176:179], v[50:53]
	v_mfma_f32_16x16x32_bf16 v[38:41], v[160:163], v[184:187], v[38:41]
	v_mfma_f32_16x16x32_bf16 v[34:37], v[168:171], v[184:187], v[34:37]
	v_mfma_f32_16x16x32_bf16 v[22:25], v[160:163], v[192:195], v[22:25]
	v_mfma_f32_16x16x32_bf16 v[18:21], v[168:171], v[192:195], v[18:21]
	v_mfma_f32_16x16x32_bf16 v[4:7], v[160:163], v[200:203], v[4:7]
	v_mfma_f32_16x16x32_bf16 v[0:3], v[168:171], v[200:203], v[0:3]
	v_mfma_f32_16x16x32_bf16 v[54:57], v[164:167], v[180:183], v[54:57]
	v_mfma_f32_16x16x32_bf16 v[50:53], v[172:175], v[180:183], v[50:53]
	v_mfma_f32_16x16x32_bf16 v[38:41], v[164:167], v[188:191], v[38:41]
	v_mfma_f32_16x16x32_bf16 v[34:37], v[172:175], v[188:191], v[34:37]
	v_mfma_f32_16x16x32_bf16 v[22:25], v[164:167], v[196:199], v[22:25]
	v_mfma_f32_16x16x32_bf16 v[18:21], v[172:175], v[196:199], v[18:21]
	v_mfma_f32_16x16x32_bf16 v[4:7], v[164:167], v[210:213], v[4:7]
	v_mfma_f32_16x16x32_bf16 v[0:3], v[172:175], v[210:213], v[0:3]
	s_setprio 0
	s_barrier
	s_add_i32 s37, s37, 2
	s_add_u32 s34, s34, 0x100
	s_addc_u32 s35, s35, 0
	s_add_u32 s39, s39, 0x100
	s_addc_u32 s36, s36, 0
	s_cmp_gt_u32 s37, 13
	s_cbranch_scc0 .LBB0_835
	s_and_b64 vcc, exec, s[12:13]
	s_cbranch_vccz .LBB0_838
	s_barrier
